# baseline (speedup 1.0000x reference)
; __device__ __forceinline__ void attn_blk(bool ctx_too, const bf16_t* U, bf16_t* Y, const float* nb_l, LAS unsigned char* lds, int lane, int wave, int tid) {
;     ...
;         for (int sp = 0; sp < nsteps; sp += 2) {
;         { const int st = sp; if (st < nsteps) { const int cur = st & 1;
;             if (st + 2 < nsteps) { const int s2 = st + 2; const int trow = (s2 < 4) ? (ML + b * CTXL + 64 * s2) : (b * SEQ + (lo + s2 - 4) * 64);
;                 const bf16_t* kv = U + (size_t)(trow + srow) * NU + 64 * h + 8 * schunk; kA = *(const u32x4*)(kv + UC_K); vA = *(const u32x4*)(kv + UC_V); }
.LBB0_481:
	s_add_i32 s86, s85, -1
	s_cmp_lt_i32 s86, s43
	s_cselect_b64 s[6:7], -1, 0
	s_cmp_ge_i32 s86, s43
	s_cbranch_scc1 .LBB0_483
	s_sub_i32 s0, s84, 64
	s_cmp_eq_u32 s85, 3
	s_cselect_b32 s0, s46, s0
	v_add_u32_e32 v0, s0, v147
	v_mad_i64_i32 v[0:1], s[0:1], v0, s50, v[144:145]
	global_load_dwordx4 v[116:119], v[0:1], off offset:2560
	global_load_dwordx4 v[120:123], v[0:1], off offset:3584

; #define LAS __attribute__((address_space(3)))
; __device__ __forceinline__ void attn_blk(bool ctx_too, const bf16_t* U, bf16_t* Y, const float* nb_l, LAS unsigned char* lds, int lane, int wave, int tid) {
;     ...
;             if (st + 1 < nsteps) { *(LAS u32x4*)(lds + 16384 + (cur ^ 1) * 8192 + kst_off) = kB; *(LAS u32x4*)(lds + 32768 + (cur ^ 1) * 8192 + vst_off) = vB; }
.LBB0_501:
	s_add_i32 s1, s85, -2
	s_cmp_lt_i32 s1, s43
	s_cselect_b64 s[30:31], -1, 0
	s_cmp_ge_i32 s1, s43
	s_cbranch_scc1 .LBB0_503
	s_cmp_lg_u32 s6, 0
	s_cbranch_scc0 .Lat_w0a
	s_waitcnt vmcnt(2)
	s_branch .Lat_wja

; #define LAS __attribute__((address_space(3)))
; __device__ __forceinline__ void attn_blk(bool ctx_too, const bf16_t* U, bf16_t* Y, const float* nb_l, LAS unsigned char* lds, int lane, int wave, int tid) {
;     ...
;             if (st + 1 < nsteps) { *(LAS u32x4*)(lds + 16384 + (cur ^ 1) * 8192 + kst_off) = kB; *(LAS u32x4*)(lds + 32768 + (cur ^ 1) * 8192 + vst_off) = vB; }
;             __syncthreads(); } }
;         { const int st = sp + 1; if (st < nsteps) { const int cur = st & 1;
;             if (st + 2 < nsteps) { const int s2 = st + 2; const int trow = (s2 < 4) ? (ML + b * CTXL + 64 * s2) : (b * SEQ + (lo + s2 - 4) * 64);
;                 const bf16_t* kv = U + (size_t)(trow + srow) * NU + 64 * h + 8 * schunk; kB = *(const u32x4*)(kv + UC_K); vB = *(const u32x4*)(kv + UC_V); }
.Lat_wja:
	ds_write_b128 v193, v[124:127] offset:24576
	ds_write_b128 v194, v[128:131] offset:40960
.LBB0_503:
	s_andn2_b64 vcc, exec, s[30:31]
	s_waitcnt lgkmcnt(0)
	s_barrier
	s_cbranch_vccnz .LBB0_480
	s_cmp_ge_i32 s85, s43
	s_cbranch_scc1 .LBB0_512
	s_cmp_eq_u32 s85, 3
	s_cselect_b32 s1, s81, s84
	v_add_u32_e32 v0, s1, v147
	v_mad_i64_i32 v[0:1], s[30:31], v0, s50, v[144:145]
	global_load_dwordx4 v[124:127], v[0:1], off offset:2560
	global_load_dwordx4 v[128:131], v[0:1], off offset:3584
	s_andn2_b64 vcc, exec, s[26:27]
	s_cbranch_vccz .LBB0_513

; #define LAS __attribute__((address_space(3)))
; __device__ __forceinline__ void attn_blk(bool ctx_too, const bf16_t* U, bf16_t* Y, const float* nb_l, LAS unsigned char* lds, int lane, int wave, int tid) {
;     ...
;             if (st + 1 < nsteps) { *(LAS u32x4*)(lds + 16384 + (cur ^ 1) * 8192 + kst_off) = kA; *(LAS u32x4*)(lds + 32768 + (cur ^ 1) * 8192 + vst_off) = vA; }
.LBB0_525:
	s_cmp_lt_i32 s85, s43
	s_cbranch_scc0 .Lat_w0b
	s_waitcnt vmcnt(2)
	s_branch .Lat_wjb

; #define LAS __attribute__((address_space(3)))
; __device__ __forceinline__ void attn_blk(bool ctx_too, const bf16_t* U, bf16_t* Y, const float* nb_l, LAS unsigned char* lds, int lane, int wave, int tid) {
;     ...
;             if (st + 1 < nsteps) { *(LAS u32x4*)(lds + 16384 + (cur ^ 1) * 8192 + kst_off) = kA; *(LAS u32x4*)(lds + 32768 + (cur ^ 1) * 8192 + vst_off) = vA; }
.Lat_wjb:
	ds_write_b128 v193, v[116:119] offset:16384
	ds_write_b128 v194, v[120:123] offset:32768
	s_branch .LBB0_479
